# k32 + 64-byte alignment of the 10 GEMM K-loop headers (code placement)
# speedup vs baseline: 1.0030x; 1.0030x over previous
.Lzb_0_1:
	s_barrier
	s_add_i32 s45, 0, 0x18000
	s_add_i32 s47, 0, 0x1c000
	v_add_u32_e32 v162, s45, v147
	v_add_u32_e32 v178, s47, v147
	ds_read_b128 v[148:151], v162
	ds_read_b128 v[152:155], v162 offset:1024
	ds_read_b128 v[158:161], v162 offset:2048
	ds_read_b128 v[162:165], v162 offset:3072
	ds_read_b128 v[166:169], v178
	ds_read_b128 v[170:173], v178 offset:1024
	ds_read_b128 v[174:177], v178 offset:2048
	ds_read_b128 v[178:181], v178 offset:3072
	s_add_u32 s54, s54, 0x80000
	s_addc_u32 s55, s55, 0
	s_mov_b32 m0, s59
	v_lshl_add_u64 v[218:219], s[54:55], 0, v[136:137]
	ds_read_b128 v[182:185], v157 offset:32768
	ds_read_b128 v[186:189], v157 offset:33792
	ds_read_b128 v[190:193], v157 offset:34816
	ds_read_b128 v[194:197], v157 offset:35840
	ds_read_b128 v[198:201], v157 offset:36864
	ds_read_b128 v[202:205], v157 offset:37888
	ds_read_b128 v[206:209], v157 offset:38912
	ds_read_b128 v[210:213], v157 offset:39936
	global_load_lds_dwordx4 v[218:219], off
	v_lshl_add_u64 v[218:219], s[54:55], 0, v[134:135]
	s_mov_b32 m0, s60
	s_nop 0
	global_load_lds_dwordx4 v[218:219], off
	s_waitcnt vmcnt(8)
	s_waitcnt lgkmcnt(0)
	s_barrier
	s_setprio 3
	s_waitcnt lgkmcnt(0)
	v_mfma_i32_16x16x64_i8 v[126:129], v[148:151], v[182:185], v[126:129]
	v_mfma_i32_16x16x64_i8 v[118:121], v[158:161], v[182:185], v[118:121]
	v_mfma_i32_16x16x64_i8 v[102:105], v[158:161], v[190:193], v[102:105]
	v_mfma_i32_16x16x64_i8 v[110:113], v[148:151], v[190:193], v[110:113]
	v_mfma_i32_16x16x64_i8 v[94:97], v[148:151], v[198:201], v[94:97]
	v_mfma_i32_16x16x64_i8 v[86:89], v[158:161], v[198:201], v[86:89]
	v_mfma_i32_16x16x64_i8 v[70:73], v[158:161], v[206:209], v[70:73]
	v_mfma_i32_16x16x64_i8 v[78:81], v[148:151], v[206:209], v[78:81]
	v_mfma_i32_16x16x64_i8 v[126:129], v[152:155], v[186:189], v[126:129]
	v_mfma_i32_16x16x64_i8 v[118:121], v[162:165], v[186:189], v[118:121]
	v_mfma_i32_16x16x64_i8 v[102:105], v[162:165], v[194:197], v[102:105]
	v_mfma_i32_16x16x64_i8 v[110:113], v[152:155], v[194:197], v[110:113]
	v_mfma_i32_16x16x64_i8 v[94:97], v[152:155], v[202:205], v[94:97]
	v_mfma_i32_16x16x64_i8 v[86:89], v[162:165], v[202:205], v[86:89]
	v_mfma_i32_16x16x64_i8 v[70:73], v[162:165], v[210:213], v[70:73]
	v_mfma_i32_16x16x64_i8 v[78:81], v[152:155], v[210:213], v[78:81]
	s_setprio 0
	s_setprio 3
	v_mfma_i32_16x16x64_i8 v[122:125], v[166:169], v[182:185], v[122:125]
	v_mfma_i32_16x16x64_i8 v[114:117], v[174:177], v[182:185], v[114:117]
	v_mfma_i32_16x16x64_i8 v[98:101], v[174:177], v[190:193], v[98:101]
	v_mfma_i32_16x16x64_i8 v[106:109], v[166:169], v[190:193], v[106:109]
	v_mfma_i32_16x16x64_i8 v[90:93], v[166:169], v[198:201], v[90:93]
	v_mfma_i32_16x16x64_i8 v[82:85], v[174:177], v[198:201], v[82:85]
	v_mfma_i32_16x16x64_i8 v[66:69], v[174:177], v[206:209], v[66:69]
	v_mfma_i32_16x16x64_i8 v[74:77], v[166:169], v[206:209], v[74:77]
	v_mfma_i32_16x16x64_i8 v[122:125], v[170:173], v[186:189], v[122:125]
	v_mfma_i32_16x16x64_i8 v[114:117], v[178:181], v[186:189], v[114:117]
	v_mfma_i32_16x16x64_i8 v[98:101], v[178:181], v[194:197], v[98:101]
	v_mfma_i32_16x16x64_i8 v[106:109], v[170:173], v[194:197], v[106:109]
	v_mfma_i32_16x16x64_i8 v[90:93], v[170:173], v[202:205], v[90:93]
	v_mfma_i32_16x16x64_i8 v[82:85], v[178:181], v[202:205], v[82:85]
	v_mfma_i32_16x16x64_i8 v[66:69], v[178:181], v[210:213], v[66:69]
	v_mfma_i32_16x16x64_i8 v[74:77], v[170:173], v[210:213], v[74:77]
	s_setprio 0
	s_barrier
	s_add_u32 s54, s52, 0x4000
	s_addc_u32 s55, s53, 0
	s_add_i32 s45, s45, s43
	v_lshl_add_u64 v[218:219], s[54:55], 0, v[130:131]
	s_mov_b32 m0, s45
	ds_read_b128 v[182:185], v157 offset:49152
	ds_read_b128 v[186:189], v157 offset:50176
	ds_read_b128 v[190:193], v157 offset:51200
	ds_read_b128 v[194:197], v157 offset:52224
	ds_read_b128 v[198:201], v157 offset:53248
	ds_read_b128 v[202:205], v157 offset:54272
	ds_read_b128 v[206:209], v157 offset:55296
	ds_read_b128 v[210:213], v157 offset:56320
	global_load_lds_dwordx4 v[218:219], off
	s_add_i32 m0, s45, 0x2000
	s_add_u32 s52, s52, 0x84000
	v_lshl_add_u64 v[218:219], s[54:55], 0, v[132:133]
	s_addc_u32 s53, s53, 0
	s_add_i32 s45, s47, s43
	global_load_lds_dwordx4 v[218:219], off
	v_lshl_add_u64 v[218:219], s[52:53], 0, v[130:131]
	s_mov_b32 m0, s45
	v_lshl_add_u64 v[214:215], v[214:215], 0, s[38:39]
	global_load_lds_dwordx4 v[218:219], off
	v_lshl_add_u64 v[218:219], s[52:53], 0, v[132:133]
	s_add_i32 m0, s45, 0x2000
	s_nop 0
	global_load_lds_dwordx4 v[218:219], off
	s_mov_b32 m0, s64
	s_nop 0
	global_load_lds_dwordx4 v[214:215], off
	v_lshl_add_u64 v[214:215], v[216:217], 0, s[38:39]
	s_mov_b32 m0, s65
	s_nop 0
	global_load_lds_dwordx4 v[214:215], off
	s_waitcnt vmcnt(8)
	s_waitcnt lgkmcnt(0)
	s_barrier
	s_setprio 3
	s_waitcnt lgkmcnt(0)
	v_mfma_i32_16x16x64_i8 v[62:65], v[148:151], v[182:185], v[62:65]
	v_mfma_i32_16x16x64_i8 v[54:57], v[158:161], v[182:185], v[54:57]
	v_mfma_i32_16x16x64_i8 v[38:41], v[158:161], v[190:193], v[38:41]
	v_mfma_i32_16x16x64_i8 v[46:49], v[148:151], v[190:193], v[46:49]
	v_mfma_i32_16x16x64_i8 v[30:33], v[148:151], v[198:201], v[30:33]
	v_mfma_i32_16x16x64_i8 v[22:25], v[158:161], v[198:201], v[22:25]
	v_mfma_i32_16x16x64_i8 v[6:9], v[158:161], v[206:209], v[6:9]
	v_mfma_i32_16x16x64_i8 v[14:17], v[148:151], v[206:209], v[14:17]
	v_mfma_i32_16x16x64_i8 v[62:65], v[152:155], v[186:189], v[62:65]
	v_mfma_i32_16x16x64_i8 v[54:57], v[162:165], v[186:189], v[54:57]
	v_mfma_i32_16x16x64_i8 v[38:41], v[162:165], v[194:197], v[38:41]
	v_mfma_i32_16x16x64_i8 v[46:49], v[152:155], v[194:197], v[46:49]
	v_mfma_i32_16x16x64_i8 v[30:33], v[152:155], v[202:205], v[30:33]
	v_mfma_i32_16x16x64_i8 v[22:25], v[162:165], v[202:205], v[22:25]
	v_mfma_i32_16x16x64_i8 v[6:9], v[162:165], v[210:213], v[6:9]
	v_mfma_i32_16x16x64_i8 v[14:17], v[152:155], v[210:213], v[14:17]
	s_setprio 0
	s_setprio 3
	v_mfma_i32_16x16x64_i8 v[58:61], v[166:169], v[182:185], v[58:61]
	v_mfma_i32_16x16x64_i8 v[50:53], v[174:177], v[182:185], v[50:53]
	v_mfma_i32_16x16x64_i8 v[34:37], v[174:177], v[190:193], v[34:37]
	v_mfma_i32_16x16x64_i8 v[42:45], v[166:169], v[190:193], v[42:45]
	v_mfma_i32_16x16x64_i8 v[26:29], v[166:169], v[198:201], v[26:29]
	v_mfma_i32_16x16x64_i8 v[18:21], v[174:177], v[198:201], v[18:21]
	v_mfma_i32_16x16x64_i8 v[2:5], v[174:177], v[206:209], v[2:5]
	v_mfma_i32_16x16x64_i8 v[10:13], v[166:169], v[206:209], v[10:13]
	v_mfma_i32_16x16x64_i8 v[58:61], v[170:173], v[186:189], v[58:61]
	v_mfma_i32_16x16x64_i8 v[50:53], v[178:181], v[186:189], v[50:53]
	v_mfma_i32_16x16x64_i8 v[34:37], v[178:181], v[194:197], v[34:37]
	v_mfma_i32_16x16x64_i8 v[42:45], v[170:173], v[194:197], v[42:45]
	v_mfma_i32_16x16x64_i8 v[26:29], v[170:173], v[202:205], v[26:29]
	v_mfma_i32_16x16x64_i8 v[18:21], v[178:181], v[202:205], v[18:21]
	v_mfma_i32_16x16x64_i8 v[2:5], v[178:181], v[210:213], v[2:5]
	v_mfma_i32_16x16x64_i8 v[10:13], v[170:173], v[210:213], v[10:13]
	s_setprio 0
	s_barrier
	s_add_i32 s75, s75, 2
	s_add_u32 s73, s73, 0x8000
	s_addc_u32 s74, s74, 0
	s_add_u32 s50, s50, 0x100
	s_addc_u32 s51, s51, 0
	s_cmp_gt_u32 s75, 29
	s_cbranch_scc1 .LBB0_209
	.p2align	6

.LBB0_408:
	s_add_u32 s75, s48, 0x8000
	s_addc_u32 s76, s49, 0
	s_mov_b32 s77, -2
	.p2align	6

.LBB0_557:
	s_add_u32 s41, s48, 0x8000
	s_addc_u32 s43, s49, 0
	s_mov_b32 s67, -2
	.p2align	6

.LBB0_583:
	s_add_u32 s39, s0, 0x8000
	s_addc_u32 s41, s1, 0
	s_add_u32 s0, s46, 0x100080
	s_addc_u32 s1, s47, 0
	s_mov_b32 s64, -2
	.p2align	6

.LBB0_609:
	s_add_u32 s41, s50, 0x8000
	s_addc_u32 s43, s51, 0
	s_mov_b32 s68, -2
	.p2align	6

.LBB0_1102:
	v_mov_b32_e32 v2, 0
	s_mov_b32 s45, 0
	s_mov_b64 s[0:1], -1
	s_mov_b64 s[54:55], 0
	v_mov_b32_e32 v3, v2
	v_mov_b32_e32 v4, v2
	v_mov_b32_e32 v5, v2
	v_mov_b32_e32 v6, v2
	v_mov_b32_e32 v7, v2
	v_mov_b32_e32 v8, v2
	v_mov_b32_e32 v9, v2
	v_mov_b32_e32 v10, v2
	v_mov_b32_e32 v11, v2
	v_mov_b32_e32 v12, v2
	v_mov_b32_e32 v13, v2
	v_mov_b32_e32 v14, v2
	v_mov_b32_e32 v15, v2
	v_mov_b32_e32 v16, v2
	v_mov_b32_e32 v17, v2
	v_mov_b32_e32 v18, v2
	v_mov_b32_e32 v19, v2
	v_mov_b32_e32 v20, v2
	v_mov_b32_e32 v21, v2
	v_mov_b32_e32 v22, v2
	v_mov_b32_e32 v23, v2
	v_mov_b32_e32 v24, v2
	v_mov_b32_e32 v25, v2
	v_mov_b32_e32 v26, v2
	v_mov_b32_e32 v27, v2
	v_mov_b32_e32 v28, v2
	v_mov_b32_e32 v29, v2
	v_mov_b32_e32 v30, v2
	v_mov_b32_e32 v31, v2
	v_mov_b32_e32 v32, v2
	v_mov_b32_e32 v33, v2
	v_mov_b32_e32 v58, v2
	v_mov_b32_e32 v59, v2
	v_mov_b32_e32 v60, v2
	v_mov_b32_e32 v61, v2
	v_mov_b32_e32 v62, v2
	v_mov_b32_e32 v63, v2
	v_mov_b32_e32 v64, v2
	v_mov_b32_e32 v65, v2
	v_mov_b32_e32 v74, v2
	v_mov_b32_e32 v75, v2
	v_mov_b32_e32 v76, v2
	v_mov_b32_e32 v77, v2
	v_mov_b32_e32 v78, v2
	v_mov_b32_e32 v79, v2
	v_mov_b32_e32 v80, v2
	v_mov_b32_e32 v81, v2
	v_mov_b32_e32 v82, v2
	v_mov_b32_e32 v83, v2
	v_mov_b32_e32 v84, v2
	v_mov_b32_e32 v85, v2
	v_mov_b32_e32 v86, v2
	v_mov_b32_e32 v87, v2
	v_mov_b32_e32 v88, v2
	v_mov_b32_e32 v89, v2
	v_mov_b32_e32 v90, v2
	v_mov_b32_e32 v91, v2
	v_mov_b32_e32 v92, v2
	v_mov_b32_e32 v93, v2
	v_mov_b32_e32 v94, v2
	v_mov_b32_e32 v95, v2
	v_mov_b32_e32 v96, v2
	v_mov_b32_e32 v97, v2
	v_mov_b32_e32 v34, v2
	v_mov_b32_e32 v35, v2
	v_mov_b32_e32 v36, v2
	v_mov_b32_e32 v37, v2
	v_mov_b32_e32 v38, v2
	v_mov_b32_e32 v39, v2
	v_mov_b32_e32 v40, v2
	v_mov_b32_e32 v41, v2
	v_mov_b32_e32 v42, v2
	v_mov_b32_e32 v43, v2
	v_mov_b32_e32 v44, v2
	v_mov_b32_e32 v45, v2
	v_mov_b32_e32 v46, v2
	v_mov_b32_e32 v47, v2
	v_mov_b32_e32 v48, v2
	v_mov_b32_e32 v49, v2
	v_mov_b32_e32 v50, v2
	v_mov_b32_e32 v51, v2
	v_mov_b32_e32 v52, v2
	v_mov_b32_e32 v53, v2
	v_mov_b32_e32 v54, v2
	v_mov_b32_e32 v55, v2
	v_mov_b32_e32 v56, v2
	v_mov_b32_e32 v57, v2
	v_mov_b32_e32 v66, v2
	v_mov_b32_e32 v67, v2
	v_mov_b32_e32 v68, v2
	v_mov_b32_e32 v69, v2
	v_mov_b32_e32 v70, v2
	v_mov_b32_e32 v71, v2
	v_mov_b32_e32 v72, v2
	v_mov_b32_e32 v73, v2
	v_mov_b32_e32 v98, v2
	v_mov_b32_e32 v99, v2
	v_mov_b32_e32 v100, v2
	v_mov_b32_e32 v101, v2
	v_mov_b32_e32 v102, v2
	v_mov_b32_e32 v103, v2
	v_mov_b32_e32 v104, v2
	v_mov_b32_e32 v105, v2
	v_mov_b32_e32 v106, v2
	v_mov_b32_e32 v107, v2
	v_mov_b32_e32 v108, v2
	v_mov_b32_e32 v109, v2
	v_mov_b32_e32 v110, v2
	v_mov_b32_e32 v111, v2
	v_mov_b32_e32 v112, v2
	v_mov_b32_e32 v113, v2
	v_mov_b32_e32 v114, v2
	v_mov_b32_e32 v115, v2
	v_mov_b32_e32 v116, v2
	v_mov_b32_e32 v117, v2
	v_mov_b32_e32 v118, v2
	v_mov_b32_e32 v119, v2
	v_mov_b32_e32 v120, v2
	v_mov_b32_e32 v121, v2
	v_mov_b32_e32 v122, v2
	v_mov_b32_e32 v123, v2
	v_mov_b32_e32 v124, v2
	v_mov_b32_e32 v125, v2
	v_mov_b32_e32 v126, v2
	v_mov_b32_e32 v127, v2
	v_mov_b32_e32 v128, v2
	v_mov_b32_e32 v129, v2
	.p2align	6

.LBB0_1183:
	s_add_u32 s43, s0, 0x8000
	s_addc_u32 s45, s1, 0
	s_add_u32 s0, s50, 0x40080
	s_addc_u32 s1, s51, 0
	s_mov_b32 s73, -2
	.p2align	6

.LBB0_1270:
	s_add_u32 s45, s0, 0x8000
	s_addc_u32 s47, s1, 0
	s_add_u32 s0, s52, 0x100080
	s_addc_u32 s1, s53, 0
	s_mov_b32 s73, -2
	.p2align	6

.LBB0_1426:
	s_add_u32 s78, s10, 0x8000
	s_addc_u32 s79, s11, 0
	s_add_u32 s54, s16, 0x80080
	s_addc_u32 s55, s17, 0
	s_mov_b32 s80, -2
	s_mov_b64 s[10:11], s[58:59]
	s_mov_b64 s[16:17], s[56:57]
	s_branch .LBB0_1428
	.p2align	6

.LBB0_1599:
	s_add_u32 s68, s42, 0x8000
	s_addc_u32 s69, s43, 0
	s_mov_b32 s70, -2
	.p2align	6
